# next-tile L2 warm-up: after each K-loop in phases 1 and 7 the workgroup touches the lines of its next tile's first K-step (same A rows, B 8 n-tiles on) with dummy loads so that tile's prologue loads h
# baseline (speedup 1.0000x reference)
.LBB0_104:
	s_waitcnt lgkmcnt(0)
	s_barrier
	s_min_u32 s98, s2, 0x380
	s_waitcnt vmcnt(11)
	ds_write_b128 v243, v[160:163] offset:36864
	v_add_u32_e32 v188, s98, v200
	v_add_u32_e32 v188, 0x40, v188
	v_lshl_add_u64 v[160:161], v[188:189], 1, s[24:25]
	global_load_dwordx4 v[160:163], v[160:161], off
	s_waitcnt vmcnt(11)
	ds_write_b128 v243, v[164:167] offset:41472
	v_add_u32_e32 v188, s98, v200
	v_add_u32_e32 v188, 0x8040, v188
	v_lshl_add_u64 v[164:165], v[188:189], 1, s[24:25]
	global_load_dwordx4 v[164:167], v[164:165], off
	s_waitcnt vmcnt(11)
	ds_write_b128 v243, v[168:171] offset:46080
	v_add_u32_e32 v188, s98, v200
	v_add_u32_e32 v188, 0x10040, v188
	v_lshl_add_u64 v[168:169], v[188:189], 1, s[24:25]
	global_load_dwordx4 v[168:171], v[168:169], off
	s_waitcnt vmcnt(11)
	ds_write_b128 v243, v[172:175] offset:50688
	v_add_u32_e32 v188, s98, v200
	v_add_u32_e32 v188, 0x18040, v188
	v_lshl_add_u64 v[172:173], v[188:189], 1, s[24:25]
	global_load_dwordx4 v[172:175], v[172:173], off
	s_waitcnt vmcnt(11)
	ds_write_b128 v243, v[156:159]
	v_dot2c_f32_bf16_e32 v197, v156, v156
	v_dot2c_f32_bf16_e32 v197, v157, v157
	v_dot2c_f32_bf16_e32 v197, v158, v158
	v_dot2c_f32_bf16_e32 v197, v159, v159
	v_add_u32_e32 v188, s98, v198
	v_add_u32_e32 v188, 0x40, v188
	v_lshl_add_u64 v[156:157], v[188:189], 1, s[36:37]
	global_load_dwordx4 v[156:159], v[156:157], off
	s_waitcnt vmcnt(11)
	ds_write_b128 v243, v[152:155] offset:4608
	v_dot2c_f32_bf16_e32 v196, v152, v152
	v_dot2c_f32_bf16_e32 v196, v153, v153
	v_dot2c_f32_bf16_e32 v196, v154, v154
	v_dot2c_f32_bf16_e32 v196, v155, v155
	v_add_u32_e32 v188, s98, v198
	v_add_u32_e32 v188, 0x8040, v188
	v_lshl_add_u64 v[152:153], v[188:189], 1, s[36:37]
	global_load_dwordx4 v[152:155], v[152:153], off
	s_waitcnt vmcnt(11)
	ds_write_b128 v243, v[148:151] offset:9216
	v_dot2c_f32_bf16_e32 v195, v148, v148
	v_dot2c_f32_bf16_e32 v195, v149, v149
	v_dot2c_f32_bf16_e32 v195, v150, v150
	v_dot2c_f32_bf16_e32 v195, v151, v151
	v_add_u32_e32 v188, s98, v198
	v_add_u32_e32 v188, 0x10040, v188
	v_lshl_add_u64 v[148:149], v[188:189], 1, s[36:37]
	global_load_dwordx4 v[148:151], v[148:149], off
	s_waitcnt vmcnt(11)
	ds_write_b128 v243, v[144:147] offset:13824
	v_dot2c_f32_bf16_e32 v194, v144, v144
	v_dot2c_f32_bf16_e32 v194, v145, v145
	v_dot2c_f32_bf16_e32 v194, v146, v146
	v_dot2c_f32_bf16_e32 v194, v147, v147
	v_add_u32_e32 v188, s98, v198
	v_add_u32_e32 v188, 0x18040, v188
	v_lshl_add_u64 v[144:145], v[188:189], 1, s[36:37]
	global_load_dwordx4 v[144:147], v[144:145], off
	s_waitcnt vmcnt(11)
	ds_write_b128 v243, v[140:143] offset:18432
	v_dot2c_f32_bf16_e32 v193, v140, v140
	v_dot2c_f32_bf16_e32 v193, v141, v141
	v_dot2c_f32_bf16_e32 v193, v142, v142
	v_dot2c_f32_bf16_e32 v193, v143, v143
	v_add_u32_e32 v188, s98, v198
	v_add_u32_e32 v188, 0x20040, v188
	v_lshl_add_u64 v[140:141], v[188:189], 1, s[36:37]
	global_load_dwordx4 v[140:143], v[140:141], off
	s_waitcnt vmcnt(11)
	ds_write_b128 v243, v[136:139] offset:23040
	v_dot2c_f32_bf16_e32 v192, v136, v136
	v_dot2c_f32_bf16_e32 v192, v137, v137
	v_dot2c_f32_bf16_e32 v192, v138, v138
	v_dot2c_f32_bf16_e32 v192, v139, v139
	v_add_u32_e32 v188, s98, v198
	v_add_u32_e32 v188, 0x28040, v188
	v_lshl_add_u64 v[136:137], v[188:189], 1, s[36:37]
	global_load_dwordx4 v[136:139], v[136:137], off
	s_waitcnt vmcnt(11)
	ds_write_b128 v243, v[132:135] offset:27648
	v_dot2c_f32_bf16_e32 v191, v132, v132
	v_dot2c_f32_bf16_e32 v191, v133, v133
	v_dot2c_f32_bf16_e32 v191, v134, v134
	v_dot2c_f32_bf16_e32 v191, v135, v135
	v_add_u32_e32 v188, s98, v198
	v_add_u32_e32 v188, 0x30040, v188
	v_lshl_add_u64 v[132:133], v[188:189], 1, s[36:37]
	global_load_dwordx4 v[132:135], v[132:133], off
	s_waitcnt vmcnt(11)
	ds_write_b128 v243, v[128:131] offset:32256
	v_dot2c_f32_bf16_e32 v190, v128, v128
	v_dot2c_f32_bf16_e32 v190, v129, v129
	v_dot2c_f32_bf16_e32 v190, v130, v130
	v_dot2c_f32_bf16_e32 v190, v131, v131
	v_add_u32_e32 v188, s98, v198
	v_add_u32_e32 v188, 0x38040, v188
	v_lshl_add_u64 v[128:129], v[188:189], 1, s[36:37]
	global_load_dwordx4 v[128:131], v[128:129], off
	s_waitcnt lgkmcnt(0)
	s_barrier
	ds_read_b128 v[244:247], v242 offset:36864
	ds_read_b128 v[184:187], v242 offset:41472
	ds_read_b128 v[248:251], v201
	ds_read_b128 v[232:235], v201 offset:4608
	s_waitcnt lgkmcnt(1)
	v_mfma_f32_32x32x16_bf16 v[112:127], v[248:251], v[244:247], v[112:127]
	v_mfma_f32_32x32x16_bf16 v[96:111], v[248:251], v[184:187], v[96:111]
	ds_read_b128 v[248:251], v201 offset:9216
	s_waitcnt lgkmcnt(1)
	v_mfma_f32_32x32x16_bf16 v[80:95], v[232:235], v[244:247], v[80:95]
	v_mfma_f32_32x32x16_bf16 v[64:79], v[232:235], v[184:187], v[64:79]
	ds_read_b128 v[232:235], v199
	ds_read_b128 v[176:179], v242 offset:36896
	ds_read_b128 v[180:183], v242 offset:41504
	s_waitcnt lgkmcnt(3)
	v_mfma_f32_32x32x16_bf16 v[48:63], v[248:251], v[244:247], v[48:63]
	v_mfma_f32_32x32x16_bf16 v[32:47], v[248:251], v[184:187], v[32:47]
	ds_read_b128 v[248:251], v201 offset:32
	s_waitcnt lgkmcnt(3)
	v_mfma_f32_32x32x16_bf16 v[16:31], v[232:235], v[244:247], v[16:31]
	v_mfma_f32_32x32x16_bf16 v[0:15], v[232:235], v[184:187], v[0:15]
	ds_read_b128 v[232:235], v201 offset:4640
	s_waitcnt lgkmcnt(1)
	v_mfma_f32_32x32x16_bf16 v[112:127], v[248:251], v[176:179], v[112:127]
	v_mfma_f32_32x32x16_bf16 v[96:111], v[248:251], v[180:183], v[96:111]
	ds_read_b128 v[248:251], v201 offset:9248
	s_waitcnt lgkmcnt(1)
	v_mfma_f32_32x32x16_bf16 v[80:95], v[232:235], v[176:179], v[80:95]
	v_mfma_f32_32x32x16_bf16 v[64:79], v[232:235], v[180:183], v[64:79]
	ds_read_b128 v[232:235], v199 offset:32
	ds_read_b128 v[244:247], v242 offset:36928
	ds_read_b128 v[184:187], v242 offset:41536
	s_waitcnt lgkmcnt(3)
; template <bool NORM, bool DEEP, int MTW, int KSEG, class HOOK>
; DI void gemm_core_h(const bfu* __restrict__ A, int lda, const bfu* __restrict__ Bt, int ldb, int K, int m0, int n0,
;                     f32x16 (&acc)[MTW][2], char* smem, HOOK hook) {
;     ...
;   if (DEEP) {
;     for (int kt = 0; kt < nk; kt += 2) {
;       GEMM_STEP(ra0, rb0, kt, 2)
;       GEMM_STEP(ra1, rb1, kt + 1, 2)
;     }
;   } else {
;     for (int kt = 0; kt < nk; ++kt) {
;       GEMM_STEP(ra0, rb0, kt, 1)
;       if (KSEG > 0) { if (((kt + 1) % (KSEG > 0 ? KSEG : 1)) == 0) hook((kt + 1) / (KSEG > 0 ? KSEG : 1) - 1); }
;     }
;   }
;     ...
;   if (NORM) {
; #pragma unroll
;     for (int j = 0; j < NA; ++j) {
;       float v = ssq[j];
;       v += __shfl_xor(v, 1); v += __shfl_xor(v, 2); v += __shfl_xor(v, 4);
;       if (lkc == 0) rstd_s[lrow + 32 * j] = rsqrtf(v / (float)K + EPS);
;     }
;   }
	v_mfma_f32_32x32x16_bf16 v[48:63], v[248:251], v[176:179], v[48:63]
	v_mfma_f32_32x32x16_bf16 v[32:47], v[248:251], v[180:183], v[32:47]
	ds_read_b128 v[248:251], v201 offset:64
	s_waitcnt lgkmcnt(3)
	v_mfma_f32_32x32x16_bf16 v[16:31], v[232:235], v[176:179], v[16:31]
	v_mfma_f32_32x32x16_bf16 v[0:15], v[232:235], v[180:183], v[0:15]
	ds_read_b128 v[232:235], v201 offset:4672
	s_waitcnt lgkmcnt(1)
	v_mfma_f32_32x32x16_bf16 v[112:127], v[248:251], v[244:247], v[112:127]
	v_mfma_f32_32x32x16_bf16 v[96:111], v[248:251], v[184:187], v[96:111]
	ds_read_b128 v[248:251], v201 offset:9280
	s_waitcnt lgkmcnt(1)
	v_mfma_f32_32x32x16_bf16 v[80:95], v[232:235], v[244:247], v[80:95]
	v_mfma_f32_32x32x16_bf16 v[64:79], v[232:235], v[184:187], v[64:79]
	ds_read_b128 v[232:235], v199 offset:64
	ds_read_b128 v[176:179], v242 offset:36960
	ds_read_b128 v[180:183], v242 offset:41568
	s_waitcnt lgkmcnt(3)
	v_mfma_f32_32x32x16_bf16 v[48:63], v[248:251], v[244:247], v[48:63]
	v_mfma_f32_32x32x16_bf16 v[32:47], v[248:251], v[184:187], v[32:47]
	ds_read_b128 v[248:251], v201 offset:96
	s_waitcnt lgkmcnt(3)
	v_mfma_f32_32x32x16_bf16 v[16:31], v[232:235], v[244:247], v[16:31]
	v_mfma_f32_32x32x16_bf16 v[0:15], v[232:235], v[184:187], v[0:15]
	ds_read_b128 v[232:235], v201 offset:4704
	s_waitcnt lgkmcnt(1)
	v_mfma_f32_32x32x16_bf16 v[112:127], v[248:251], v[176:179], v[112:127]
	v_mfma_f32_32x32x16_bf16 v[96:111], v[248:251], v[180:183], v[96:111]
	ds_read_b128 v[248:251], v201 offset:9312
	s_waitcnt lgkmcnt(1)
	v_mfma_f32_32x32x16_bf16 v[80:95], v[232:235], v[176:179], v[80:95]
	v_mfma_f32_32x32x16_bf16 v[64:79], v[232:235], v[180:183], v[64:79]
	ds_read_b128 v[232:235], v199 offset:96
	s_waitcnt lgkmcnt(1)
	v_mfma_f32_32x32x16_bf16 v[48:63], v[248:251], v[176:179], v[48:63]
	v_mfma_f32_32x32x16_bf16 v[32:47], v[248:251], v[180:183], v[32:47]
	s_waitcnt lgkmcnt(0)
	v_mfma_f32_32x32x16_bf16 v[16:31], v[232:235], v[176:179], v[16:31]
	v_mfma_f32_32x32x16_bf16 v[0:15], v[232:235], v[180:183], v[0:15]
	s_add_i32 s2, s2, 64
	s_cmpk_eq_i32 s2, 0x400
	s_cbranch_scc0 .LBB0_104
	s_waitcnt vmcnt(0)
	v_add_u32_e32 v188, 0x0, v198
	v_lshl_add_u64 v[140:141], v[188:189], 1, s[36:37]
	global_load_dword v252, v[140:141], off
	v_add_u32_e32 v188, 0x8000, v198
	v_lshl_add_u64 v[140:141], v[188:189], 1, s[36:37]
	global_load_dword v252, v[140:141], off
	v_add_u32_e32 v188, 0x10000, v198
	v_lshl_add_u64 v[140:141], v[188:189], 1, s[36:37]
	global_load_dword v252, v[140:141], off
	v_add_u32_e32 v188, 0x18000, v198
	v_lshl_add_u64 v[140:141], v[188:189], 1, s[36:37]
	global_load_dword v252, v[140:141], off
	v_add_u32_e32 v188, 0x20000, v198
	v_lshl_add_u64 v[140:141], v[188:189], 1, s[36:37]
	global_load_dword v252, v[140:141], off
	v_add_u32_e32 v188, 0x28000, v198
	v_lshl_add_u64 v[140:141], v[188:189], 1, s[36:37]
	global_load_dword v252, v[140:141], off
	v_add_u32_e32 v188, 0x30000, v198
	v_lshl_add_u64 v[140:141], v[188:189], 1, s[36:37]
	global_load_dword v252, v[140:141], off
	v_add_u32_e32 v188, 0x38000, v198
	v_lshl_add_u64 v[140:141], v[188:189], 1, s[36:37]
	global_load_dword v252, v[140:141], off
	v_add_u32_e32 v188, 0x100000, v200
	v_lshl_add_u64 v[140:141], v[188:189], 1, s[24:25]
	global_load_dword v252, v[140:141], off
	v_add_u32_e32 v188, 0x108000, v200
	v_lshl_add_u64 v[140:141], v[188:189], 1, s[24:25]
	global_load_dword v252, v[140:141], off
	v_add_u32_e32 v188, 0x110000, v200
	v_lshl_add_u64 v[140:141], v[188:189], 1, s[24:25]
	global_load_dword v252, v[140:141], off
	v_add_u32_e32 v188, 0x118000, v200
	v_lshl_add_u64 v[140:141], v[188:189], 1, s[24:25]
	global_load_dword v252, v[140:141], off
	v_mbcnt_hi_u32_b32 v156, -1, v226
	v_xor_b32_e32 v156, 1, v156
	v_lshlrev_b32_e32 v156, 2, v156
	v_add_f32_dpp v197, v197, v197 quad_perm:[1,0,3,2] row_mask:0xf bank_mask:0xf
	v_add_f32_dpp v196, v196, v196 quad_perm:[1,0,3,2] row_mask:0xf bank_mask:0xf
	v_add_f32_dpp v195, v195, v195 quad_perm:[1,0,3,2] row_mask:0xf bank_mask:0xf
	v_add_f32_dpp v194, v194, v194 quad_perm:[1,0,3,2] row_mask:0xf bank_mask:0xf
	v_add_f32_dpp v193, v193, v193 quad_perm:[1,0,3,2] row_mask:0xf bank_mask:0xf
	v_add_f32_dpp v192, v192, v192 quad_perm:[1,0,3,2] row_mask:0xf bank_mask:0xf
	v_add_f32_dpp v191, v191, v191 quad_perm:[1,0,3,2] row_mask:0xf bank_mask:0xf
	v_add_f32_dpp v190, v190, v190 quad_perm:[1,0,3,2] row_mask:0xf bank_mask:0xf
	v_add_f32_dpp v197, v197, v197 quad_perm:[2,3,0,1] row_mask:0xf bank_mask:0xf
	v_add_f32_dpp v196, v196, v196 quad_perm:[2,3,0,1] row_mask:0xf bank_mask:0xf
	v_add_f32_dpp v195, v195, v195 quad_perm:[2,3,0,1] row_mask:0xf bank_mask:0xf
	v_add_f32_dpp v194, v194, v194 quad_perm:[2,3,0,1] row_mask:0xf bank_mask:0xf
	v_add_f32_dpp v193, v193, v193 quad_perm:[2,3,0,1] row_mask:0xf bank_mask:0xf
	v_add_f32_dpp v192, v192, v192 quad_perm:[2,3,0,1] row_mask:0xf bank_mask:0xf
	v_add_f32_dpp v191, v191, v191 quad_perm:[2,3,0,1] row_mask:0xf bank_mask:0xf
	v_add_f32_dpp v190, v190, v190 quad_perm:[2,3,0,1] row_mask:0xf bank_mask:0xf
	v_add_f32_dpp v197, v197, v197 row_half_mirror row_mask:0xf bank_mask:0xf
	v_add_f32_dpp v196, v196, v196 row_half_mirror row_mask:0xf bank_mask:0xf
	v_add_f32_dpp v195, v195, v195 row_half_mirror row_mask:0xf bank_mask:0xf
	v_add_f32_dpp v194, v194, v194 row_half_mirror row_mask:0xf bank_mask:0xf
	v_add_f32_dpp v193, v193, v193 row_half_mirror row_mask:0xf bank_mask:0xf
	v_add_f32_dpp v192, v192, v192 row_half_mirror row_mask:0xf bank_mask:0xf
	v_add_f32_dpp v191, v191, v191 row_half_mirror row_mask:0xf bank_mask:0xf
	v_add_f32_dpp v190, v190, v190 row_half_mirror row_mask:0xf bank_mask:0xf
	v_lshlrev_b32_e32 v136, 2, v240
	v_cmp_eq_u32_e64 s[2:3], 0, v241
	v_fmamk_f32 v128, v197, 0x3a800000, v225
	v_fmamk_f32 v129, v196, 0x3a800000, v225
	v_fmamk_f32 v130, v195, 0x3a800000, v225
	v_fmamk_f32 v131, v194, 0x3a800000, v225
	v_fmamk_f32 v132, v193, 0x3a800000, v225
	v_fmamk_f32 v133, v192, 0x3a800000, v225
	v_fmamk_f32 v134, v191, 0x3a800000, v225
	v_fmamk_f32 v135, v190, 0x3a800000, v225
	v_rsq_f32_e32 v128, v128
	v_rsq_f32_e32 v129, v129
	v_rsq_f32_e32 v130, v130
	v_rsq_f32_e32 v131, v131
	v_rsq_f32_e32 v132, v132
	v_rsq_f32_e32 v133, v133
	v_rsq_f32_e32 v134, v134
	v_rsq_f32_e32 v135, v135
	s_and_saveexec_b64 s[4:5], s[2:3]
	ds_write_b32 v136, v128 offset:55296
	ds_write_b32 v136, v129 offset:55424
	ds_write_b32 v136, v130 offset:55552
	ds_write_b32 v136, v131 offset:55680
	ds_write_b32 v136, v132 offset:55808
	ds_write_b32 v136, v133 offset:55936
	ds_write_b32 v136, v134 offset:56064
	ds_write_b32 v136, v135 offset:56192
	s_branch .LBB0_102

.LBB0_782:
	s_waitcnt lgkmcnt(0)
	s_barrier
	v_readlane_b32 s52, v253, 32
	v_readlane_b32 s66, v253, 46
	v_readlane_b32 s67, v253, 47
	v_readlane_b32 s53, v253, 33
	v_readlane_b32 s54, v253, 34
	v_readlane_b32 s55, v253, 35
	v_readlane_b32 s56, v253, 36
	v_readlane_b32 s57, v253, 37
	v_readlane_b32 s58, v253, 38
	v_readlane_b32 s59, v253, 39
	v_readlane_b32 s60, v253, 40
	v_readlane_b32 s61, v253, 41
	v_readlane_b32 s62, v253, 42
	v_readlane_b32 s63, v253, 43
	v_readlane_b32 s64, v253, 44
	v_readlane_b32 s65, v253, 45
	s_min_u32 s98, s2, 0x380
	s_waitcnt vmcnt(11)
	ds_write_b128 v212, v[160:163] offset:36864
	v_add_u32_e32 v188, s98, v204
	v_add_u32_e32 v188, 0x40, v188
	v_lshl_add_u64 v[160:161], v[188:189], 1, s[66:67]
	global_load_dwordx4 v[160:163], v[160:161], off
	s_waitcnt vmcnt(11)
	ds_write_b128 v212, v[164:167] offset:41472
	v_add_u32_e32 v188, s98, v204
	v_add_u32_e32 v188, 0x8040, v188
	v_lshl_add_u64 v[164:165], v[188:189], 1, s[66:67]
	global_load_dwordx4 v[164:167], v[164:165], off
	s_waitcnt vmcnt(11)
	ds_write_b128 v212, v[168:171] offset:46080
	v_add_u32_e32 v188, s98, v204
	v_add_u32_e32 v188, 0x10040, v188
	v_lshl_add_u64 v[168:169], v[188:189], 1, s[66:67]
	global_load_dwordx4 v[168:171], v[168:169], off
	s_waitcnt vmcnt(11)
	ds_write_b128 v212, v[172:175] offset:50688
	v_add_u32_e32 v188, s98, v204
	v_add_u32_e32 v188, 0x18040, v188
	v_lshl_add_u64 v[172:173], v[188:189], 1, s[66:67]
	global_load_dwordx4 v[172:175], v[172:173], off
	s_waitcnt vmcnt(11)
	ds_write_b128 v212, v[156:159]
	v_dot2c_f32_bf16_e32 v201, v156, v156
	v_dot2c_f32_bf16_e32 v201, v157, v157
	v_dot2c_f32_bf16_e32 v201, v158, v158
	v_dot2c_f32_bf16_e32 v201, v159, v159
	v_add_u32_e32 v188, s98, v202
	v_add_u32_e32 v188, 0x40, v188
	v_lshl_add_u64 v[156:157], v[188:189], 1, s[38:39]
	global_load_dwordx4 v[156:159], v[156:157], off
	s_waitcnt vmcnt(11)
	ds_write_b128 v212, v[152:155] offset:4608
	v_dot2c_f32_bf16_e32 v200, v152, v152
	v_dot2c_f32_bf16_e32 v200, v153, v153
	v_dot2c_f32_bf16_e32 v200, v154, v154
	v_dot2c_f32_bf16_e32 v200, v155, v155
	v_add_u32_e32 v188, s98, v202
	v_add_u32_e32 v188, 0x8040, v188
	v_lshl_add_u64 v[152:153], v[188:189], 1, s[38:39]
	global_load_dwordx4 v[152:155], v[152:153], off
	s_waitcnt vmcnt(11)
	ds_write_b128 v212, v[148:151] offset:9216
	v_dot2c_f32_bf16_e32 v199, v148, v148
	v_dot2c_f32_bf16_e32 v199, v149, v149
	v_dot2c_f32_bf16_e32 v199, v150, v150
	v_dot2c_f32_bf16_e32 v199, v151, v151
	v_add_u32_e32 v188, s98, v202
	v_add_u32_e32 v188, 0x10040, v188
	v_lshl_add_u64 v[148:149], v[188:189], 1, s[38:39]
	global_load_dwordx4 v[148:151], v[148:149], off
	s_waitcnt vmcnt(11)
	ds_write_b128 v212, v[144:147] offset:13824
	v_dot2c_f32_bf16_e32 v198, v144, v144
	v_dot2c_f32_bf16_e32 v198, v145, v145
	v_dot2c_f32_bf16_e32 v198, v146, v146
	v_dot2c_f32_bf16_e32 v198, v147, v147
	v_add_u32_e32 v188, s98, v202
	v_add_u32_e32 v188, 0x18040, v188
	v_lshl_add_u64 v[144:145], v[188:189], 1, s[38:39]
	global_load_dwordx4 v[144:147], v[144:145], off
	s_waitcnt vmcnt(11)
	ds_write_b128 v212, v[140:143] offset:18432
	v_dot2c_f32_bf16_e32 v197, v140, v140
	v_dot2c_f32_bf16_e32 v197, v141, v141
	v_dot2c_f32_bf16_e32 v197, v142, v142
	v_dot2c_f32_bf16_e32 v197, v143, v143
	v_add_u32_e32 v188, s98, v202
	v_add_u32_e32 v188, 0x20040, v188
	v_lshl_add_u64 v[140:141], v[188:189], 1, s[38:39]
	global_load_dwordx4 v[140:143], v[140:141], off
	s_waitcnt vmcnt(11)
	ds_write_b128 v212, v[136:139] offset:23040
	v_dot2c_f32_bf16_e32 v196, v136, v136
	v_dot2c_f32_bf16_e32 v196, v137, v137
	v_dot2c_f32_bf16_e32 v196, v138, v138
	v_dot2c_f32_bf16_e32 v196, v139, v139
	v_add_u32_e32 v188, s98, v202
	v_add_u32_e32 v188, 0x28040, v188
	v_lshl_add_u64 v[136:137], v[188:189], 1, s[38:39]
	global_load_dwordx4 v[136:139], v[136:137], off
	s_waitcnt vmcnt(11)
	ds_write_b128 v212, v[132:135] offset:27648
	v_dot2c_f32_bf16_e32 v195, v132, v132
	v_dot2c_f32_bf16_e32 v195, v133, v133
	v_dot2c_f32_bf16_e32 v195, v134, v134
	v_dot2c_f32_bf16_e32 v195, v135, v135
	v_add_u32_e32 v188, s98, v202
	v_add_u32_e32 v188, 0x30040, v188
	v_lshl_add_u64 v[132:133], v[188:189], 1, s[38:39]
	global_load_dwordx4 v[132:135], v[132:133], off
	s_waitcnt vmcnt(11)
	ds_write_b128 v212, v[128:131] offset:32256
	v_dot2c_f32_bf16_e32 v194, v128, v128
	v_dot2c_f32_bf16_e32 v194, v129, v129
	v_dot2c_f32_bf16_e32 v194, v130, v130
	v_dot2c_f32_bf16_e32 v194, v131, v131
	v_add_u32_e32 v188, s98, v202
	v_add_u32_e32 v188, 0x38040, v188
	v_lshl_add_u64 v[128:129], v[188:189], 1, s[38:39]
	global_load_dwordx4 v[128:131], v[128:129], off
	s_waitcnt lgkmcnt(0)
	s_barrier
	ds_read_b128 v[214:217], v211 offset:36864
	ds_read_b128 v[184:187], v211 offset:41472
	ds_read_b128 v[218:221], v205
	ds_read_b128 v[238:241], v205 offset:4608
	s_waitcnt lgkmcnt(1)
	v_mfma_f32_32x32x16_bf16 v[112:127], v[218:221], v[214:217], v[112:127]
	v_mfma_f32_32x32x16_bf16 v[96:111], v[218:221], v[184:187], v[96:111]
	ds_read_b128 v[218:221], v205 offset:9216
	s_waitcnt lgkmcnt(1)
	v_mfma_f32_32x32x16_bf16 v[80:95], v[238:241], v[214:217], v[80:95]
	v_mfma_f32_32x32x16_bf16 v[64:79], v[238:241], v[184:187], v[64:79]
	ds_read_b128 v[238:241], v203
	ds_read_b128 v[176:179], v211 offset:36896
	ds_read_b128 v[180:183], v211 offset:41504
	s_waitcnt lgkmcnt(3)
	v_mfma_f32_32x32x16_bf16 v[48:63], v[218:221], v[214:217], v[48:63]
	v_mfma_f32_32x32x16_bf16 v[32:47], v[218:221], v[184:187], v[32:47]
	ds_read_b128 v[218:221], v205 offset:32
	s_waitcnt lgkmcnt(3)
	v_mfma_f32_32x32x16_bf16 v[16:31], v[238:241], v[214:217], v[16:31]
	v_mfma_f32_32x32x16_bf16 v[0:15], v[238:241], v[184:187], v[0:15]
	ds_read_b128 v[238:241], v205 offset:4640
	s_waitcnt lgkmcnt(1)
	v_mfma_f32_32x32x16_bf16 v[112:127], v[218:221], v[176:179], v[112:127]
	v_mfma_f32_32x32x16_bf16 v[96:111], v[218:221], v[180:183], v[96:111]
	ds_read_b128 v[218:221], v205 offset:9248
	s_waitcnt lgkmcnt(1)
	v_mfma_f32_32x32x16_bf16 v[80:95], v[238:241], v[176:179], v[80:95]
	v_mfma_f32_32x32x16_bf16 v[64:79], v[238:241], v[180:183], v[64:79]
	ds_read_b128 v[238:241], v203 offset:32
	ds_read_b128 v[214:217], v211 offset:36928
	ds_read_b128 v[184:187], v211 offset:41536
	s_waitcnt lgkmcnt(3)
	v_mfma_f32_32x32x16_bf16 v[48:63], v[218:221], v[176:179], v[48:63]
	v_mfma_f32_32x32x16_bf16 v[32:47], v[218:221], v[180:183], v[32:47]
	ds_read_b128 v[218:221], v205 offset:64
	s_waitcnt lgkmcnt(3)
	v_mfma_f32_32x32x16_bf16 v[16:31], v[238:241], v[176:179], v[16:31]
	v_mfma_f32_32x32x16_bf16 v[0:15], v[238:241], v[180:183], v[0:15]
	ds_read_b128 v[238:241], v205 offset:4672
	s_waitcnt lgkmcnt(1)
	v_mfma_f32_32x32x16_bf16 v[112:127], v[218:221], v[214:217], v[112:127]
	v_mfma_f32_32x32x16_bf16 v[96:111], v[218:221], v[184:187], v[96:111]
	ds_read_b128 v[218:221], v205 offset:9280
	s_waitcnt lgkmcnt(1)
	v_mfma_f32_32x32x16_bf16 v[80:95], v[238:241], v[214:217], v[80:95]
	v_mfma_f32_32x32x16_bf16 v[64:79], v[238:241], v[184:187], v[64:79]
	ds_read_b128 v[238:241], v203 offset:64
	ds_read_b128 v[176:179], v211 offset:36960
	ds_read_b128 v[180:183], v211 offset:41568
	s_waitcnt lgkmcnt(3)
	v_mfma_f32_32x32x16_bf16 v[48:63], v[218:221], v[214:217], v[48:63]
	v_mfma_f32_32x32x16_bf16 v[32:47], v[218:221], v[184:187], v[32:47]
	ds_read_b128 v[218:221], v205 offset:96
	s_waitcnt lgkmcnt(3)
	v_mfma_f32_32x32x16_bf16 v[16:31], v[238:241], v[214:217], v[16:31]
	v_mfma_f32_32x32x16_bf16 v[0:15], v[238:241], v[184:187], v[0:15]
	ds_read_b128 v[238:241], v205 offset:4704
	s_waitcnt lgkmcnt(1)
	v_mfma_f32_32x32x16_bf16 v[112:127], v[218:221], v[176:179], v[112:127]
	v_mfma_f32_32x32x16_bf16 v[96:111], v[218:221], v[180:183], v[96:111]
	ds_read_b128 v[218:221], v205 offset:9312
	s_waitcnt lgkmcnt(1)
	v_mfma_f32_32x32x16_bf16 v[80:95], v[238:241], v[176:179], v[80:95]
	v_mfma_f32_32x32x16_bf16 v[64:79], v[238:241], v[180:183], v[64:79]
	ds_read_b128 v[238:241], v203 offset:96
	s_waitcnt lgkmcnt(1)
	v_mfma_f32_32x32x16_bf16 v[48:63], v[218:221], v[176:179], v[48:63]
	v_mfma_f32_32x32x16_bf16 v[32:47], v[218:221], v[180:183], v[32:47]
	s_waitcnt lgkmcnt(0)
	v_mfma_f32_32x32x16_bf16 v[16:31], v[238:241], v[176:179], v[16:31]
	v_mfma_f32_32x32x16_bf16 v[0:15], v[238:241], v[180:183], v[0:15]
	s_add_i32 s2, s2, 64
	s_cmpk_eq_i32 s2, 0x400
	s_cbranch_scc0 .LBB0_782
; template <bool NORM, bool DEEP, int MTW, int KSEG, class HOOK>
; DI void gemm_core_h(const bfu* __restrict__ A, int lda, const bfu* __restrict__ Bt, int ldb, int K, int m0, int n0,
;                     f32x16 (&acc)[MTW][2], char* smem, HOOK hook) {
;     ...
;   if (NORM) {
; #pragma unroll
;     for (int j = 0; j < NA; ++j) {
;       float v = ssq[j];
;       v += __shfl_xor(v, 1); v += __shfl_xor(v, 2); v += __shfl_xor(v, 4);
;       if (lkc == 0) rstd_s[lrow + 32 * j] = rsqrtf(v / (float)K + EPS);
;     }
;   }
	s_waitcnt vmcnt(0)
	v_add_u32_e32 v188, 0x0, v202
	v_lshl_add_u64 v[140:141], v[188:189], 1, s[38:39]
	global_load_dword v252, v[140:141], off
	v_add_u32_e32 v188, 0x8000, v202
	v_lshl_add_u64 v[140:141], v[188:189], 1, s[38:39]
	global_load_dword v252, v[140:141], off
	v_add_u32_e32 v188, 0x10000, v202
	v_lshl_add_u64 v[140:141], v[188:189], 1, s[38:39]
	global_load_dword v252, v[140:141], off
	v_add_u32_e32 v188, 0x18000, v202
	v_lshl_add_u64 v[140:141], v[188:189], 1, s[38:39]
	global_load_dword v252, v[140:141], off
	v_add_u32_e32 v188, 0x20000, v202
	v_lshl_add_u64 v[140:141], v[188:189], 1, s[38:39]
	global_load_dword v252, v[140:141], off
	v_add_u32_e32 v188, 0x28000, v202
	v_lshl_add_u64 v[140:141], v[188:189], 1, s[38:39]
	global_load_dword v252, v[140:141], off
	v_add_u32_e32 v188, 0x30000, v202
	v_lshl_add_u64 v[140:141], v[188:189], 1, s[38:39]
	global_load_dword v252, v[140:141], off
	v_add_u32_e32 v188, 0x38000, v202
	v_lshl_add_u64 v[140:141], v[188:189], 1, s[38:39]
	global_load_dword v252, v[140:141], off
	v_add_u32_e32 v188, 0x100000, v204
	v_lshl_add_u64 v[140:141], v[188:189], 1, s[66:67]
	global_load_dword v252, v[140:141], off
	v_add_u32_e32 v188, 0x108000, v204
	v_lshl_add_u64 v[140:141], v[188:189], 1, s[66:67]
	global_load_dword v252, v[140:141], off
	v_add_u32_e32 v188, 0x110000, v204
	v_lshl_add_u64 v[140:141], v[188:189], 1, s[66:67]
	global_load_dword v252, v[140:141], off
	v_add_u32_e32 v188, 0x118000, v204
	v_lshl_add_u64 v[140:141], v[188:189], 1, s[66:67]
	global_load_dword v252, v[140:141], off
	v_add_f32_dpp v201, v201, v201 quad_perm:[1,0,3,2] row_mask:0xf bank_mask:0xf
	v_add_f32_dpp v200, v200, v200 quad_perm:[1,0,3,2] row_mask:0xf bank_mask:0xf
	v_add_f32_dpp v199, v199, v199 quad_perm:[1,0,3,2] row_mask:0xf bank_mask:0xf
	v_add_f32_dpp v198, v198, v198 quad_perm:[1,0,3,2] row_mask:0xf bank_mask:0xf
	v_add_f32_dpp v197, v197, v197 quad_perm:[1,0,3,2] row_mask:0xf bank_mask:0xf
	v_add_f32_dpp v196, v196, v196 quad_perm:[1,0,3,2] row_mask:0xf bank_mask:0xf
	v_add_f32_dpp v195, v195, v195 quad_perm:[1,0,3,2] row_mask:0xf bank_mask:0xf
	v_add_f32_dpp v194, v194, v194 quad_perm:[1,0,3,2] row_mask:0xf bank_mask:0xf
	v_add_f32_dpp v201, v201, v201 quad_perm:[2,3,0,1] row_mask:0xf bank_mask:0xf
	v_add_f32_dpp v200, v200, v200 quad_perm:[2,3,0,1] row_mask:0xf bank_mask:0xf
	v_add_f32_dpp v199, v199, v199 quad_perm:[2,3,0,1] row_mask:0xf bank_mask:0xf
	v_add_f32_dpp v198, v198, v198 quad_perm:[2,3,0,1] row_mask:0xf bank_mask:0xf
	v_add_f32_dpp v197, v197, v197 quad_perm:[2,3,0,1] row_mask:0xf bank_mask:0xf
	v_add_f32_dpp v196, v196, v196 quad_perm:[2,3,0,1] row_mask:0xf bank_mask:0xf
	v_add_f32_dpp v195, v195, v195 quad_perm:[2,3,0,1] row_mask:0xf bank_mask:0xf
	v_add_f32_dpp v194, v194, v194 quad_perm:[2,3,0,1] row_mask:0xf bank_mask:0xf
	v_add_f32_dpp v201, v201, v201 row_half_mirror row_mask:0xf bank_mask:0xf
	v_add_f32_dpp v200, v200, v200 row_half_mirror row_mask:0xf bank_mask:0xf
	v_add_f32_dpp v199, v199, v199 row_half_mirror row_mask:0xf bank_mask:0xf
	v_add_f32_dpp v198, v198, v198 row_half_mirror row_mask:0xf bank_mask:0xf
	v_add_f32_dpp v197, v197, v197 row_half_mirror row_mask:0xf bank_mask:0xf
	v_add_f32_dpp v196, v196, v196 row_half_mirror row_mask:0xf bank_mask:0xf
	v_add_f32_dpp v195, v195, v195 row_half_mirror row_mask:0xf bank_mask:0xf
	v_add_f32_dpp v194, v194, v194 row_half_mirror row_mask:0xf bank_mask:0xf
	v_lshlrev_b32_e32 v136, 2, v193
	v_cmp_eq_u32_e32 vcc, 0, v210
	v_fmamk_f32 v128, v201, 0x3a800000, v225
	v_fmamk_f32 v129, v200, 0x3a800000, v225
	v_fmamk_f32 v130, v199, 0x3a800000, v225
	v_fmamk_f32 v131, v198, 0x3a800000, v225
	v_fmamk_f32 v132, v197, 0x3a800000, v225
	v_fmamk_f32 v133, v196, 0x3a800000, v225
	v_fmamk_f32 v134, v195, 0x3a800000, v225
	v_fmamk_f32 v135, v194, 0x3a800000, v225
	v_rsq_f32_e32 v128, v128
	v_rsq_f32_e32 v129, v129
	v_rsq_f32_e32 v130, v130
	v_rsq_f32_e32 v131, v131
	v_rsq_f32_e32 v132, v132
	v_rsq_f32_e32 v133, v133
	v_rsq_f32_e32 v134, v134
	v_rsq_f32_e32 v135, v135
	s_and_saveexec_b64 s[2:3], vcc
	ds_write_b32 v136, v128 offset:55296
	ds_write_b32 v136, v129 offset:55424
	ds_write_b32 v136, v130 offset:55552
	ds_write_b32 v136, v131 offset:55680
	ds_write_b32 v136, v132 offset:55808
	ds_write_b32 v136, v133 offset:55936
	ds_write_b32 v136, v134 offset:56064
	ds_write_b32 v136, v135 offset:56192
